# w_cq rows: counted wait before the first row so the second row's loads stay in flight
# baseline (speedup 1.0000x reference)
.LBB0_216:
	s_waitcnt vmcnt(0)
	v_mov_b64_e32 v[6:7], s[92:93]
	flat_load_dwordx2 v[2:3], v[6:7] offset:64 sc0 sc1
	flat_load_dwordx2 v[130:131], v[6:7] offset:80 sc0 sc1
	s_waitcnt vmcnt(0)
	s_lshl_b32 s0, s25, 4
	s_lshl_b32 s1, s24, 1
	s_add_i32 s0, s0, s1
	s_ashr_i32 s1, s0, 31
	s_lshl_b64 s[4:5], s[0:1], 2
	s_lshl_b64 s[6:7], s[0:1], 14
	v_lshlrev_b64 v[8:9], 4, v[134:135]
	v_lshl_add_u64 v[12:13], v[134:135], 3, s[14:15]
	s_lshl_b32 s10, s24, 12
	s_and_b32 s10, s10, 0x1000
	s_waitcnt lgkmcnt(0)
	v_lshl_add_u64 v[2:3], v[2:3], 0, s[4:5]
	flat_load_dword v18, v[2:3]
	global_load_dword v128, v[2:3], off offset:4
	s_nop 0
	v_lshl_add_u64 v[2:3], v[130:131], 0, s[6:7]
	v_lshl_add_u64 v[10:11], v[2:3], 0, v[8:9]
	v_add_co_u32_e32 v212, vcc, 0x1000, v10
	s_nop 1
	v_addc_co_u32_e32 v213, vcc, 0, v11, vcc
	v_add_co_u32_e32 v228, vcc, 0x2000, v10
	s_nop 1
	v_addc_co_u32_e32 v229, vcc, 0, v11, vcc
	v_add_co_u32_e32 v244, vcc, 0x3000, v10
	s_nop 1
	v_addc_co_u32_e32 v245, vcc, 0, v11, vcc
	global_load_dwordx4 v[184:187], v[10:11], off nt
	global_load_dwordx4 v[188:191], v[10:11], off offset:1024 nt
	global_load_dwordx4 v[192:195], v[10:11], off offset:2048 nt
	global_load_dwordx4 v[196:199], v[10:11], off offset:3072 nt
	global_load_dwordx4 v[200:203], v[212:213], off nt
	global_load_dwordx4 v[204:207], v[212:213], off offset:1024 nt
	global_load_dwordx4 v[208:211], v[212:213], off offset:2048 nt
	global_load_dwordx4 v[212:215], v[212:213], off offset:3072 nt
	global_load_dwordx4 v[216:219], v[228:229], off nt
	global_load_dwordx4 v[220:223], v[228:229], off offset:1024 nt
	global_load_dwordx4 v[224:227], v[228:229], off offset:2048 nt
	global_load_dwordx4 v[228:231], v[228:229], off offset:3072 nt
	global_load_dwordx4 v[232:235], v[244:245], off nt
	global_load_dwordx4 v[236:239], v[244:245], off offset:1024 nt
	global_load_dwordx4 v[240:243], v[244:245], off offset:2048 nt
	global_load_dwordx4 v[244:247], v[244:245], off offset:3072 nt
	v_add_co_u32_e32 v76, vcc, 0x4000, v10
	s_nop 1
	v_addc_co_u32_e32 v77, vcc, 0, v11, vcc
	v_add_co_u32_e32 v92, vcc, 0x5000, v10
	s_nop 1
	v_addc_co_u32_e32 v93, vcc, 0, v11, vcc
	v_add_co_u32_e32 v108, vcc, 0x6000, v10
	s_nop 1
	v_addc_co_u32_e32 v109, vcc, 0, v11, vcc
	v_add_co_u32_e32 v124, vcc, 0x7000, v10
	s_nop 1
	v_addc_co_u32_e32 v125, vcc, 0, v11, vcc
	global_load_dwordx4 v[64:67], v[76:77], off nt
	global_load_dwordx4 v[68:71], v[76:77], off offset:1024 nt
	global_load_dwordx4 v[72:75], v[76:77], off offset:2048 nt
	global_load_dwordx4 v[76:79], v[76:77], off offset:3072 nt
	global_load_dwordx4 v[80:83], v[92:93], off nt
	global_load_dwordx4 v[84:87], v[92:93], off offset:1024 nt
	global_load_dwordx4 v[88:91], v[92:93], off offset:2048 nt
	global_load_dwordx4 v[92:95], v[92:93], off offset:3072 nt
	global_load_dwordx4 v[96:99], v[108:109], off nt
	global_load_dwordx4 v[100:103], v[108:109], off offset:1024 nt
	global_load_dwordx4 v[104:107], v[108:109], off offset:2048 nt
	global_load_dwordx4 v[108:111], v[108:109], off offset:3072 nt
	global_load_dwordx4 v[112:115], v[124:125], off nt
	global_load_dwordx4 v[116:119], v[124:125], off offset:1024 nt
	global_load_dwordx4 v[120:123], v[124:125], off offset:2048 nt
	global_load_dwordx4 v[124:127], v[124:125], off offset:3072 nt
	s_lshl_b64 s[6:7], s[0:1], 13
	v_lshl_add_u64 v[14:15], v[12:13], 0, s[6:7]
	s_movk_i32 s1, 0x1000
	v_add_co_u32_e32 v16, vcc, s1, v10
	s_movk_i32 s6, 0x2000
	s_nop 0
	v_addc_co_u32_e32 v17, vcc, 0, v11, vcc
	s_movk_i32 s7, 0x3000
	s_waitcnt vmcnt(16) lgkmcnt(0)
	v_mov_b32_e32 v2, v184
	v_mov_b32_e32 v3, v185
	v_mov_b32_e32 v4, v186
	v_mov_b32_e32 v5, v187
	v_mul_f32_e32 v2, v18, v2
	v_mul_f32_e32 v3, v18, v3
	v_mul_f32_e32 v4, v18, v4
	v_mul_f32_e32 v5, v18, v5
	v_cvt_pk_bf16_f32 v2, v2, v3
	v_cvt_pk_bf16_f32 v3, v4, v5
	global_store_dwordx2 v[14:15], v[2:3], off
	s_nop 1
	v_mov_b32_e32 v2, v188
	v_mov_b32_e32 v3, v189
	v_mov_b32_e32 v4, v190
	v_mov_b32_e32 v5, v191
	v_mul_f32_e32 v2, v18, v2
	v_mul_f32_e32 v3, v18, v3
	v_mul_f32_e32 v4, v18, v4
	v_mul_f32_e32 v5, v18, v5
	v_cvt_pk_bf16_f32 v2, v2, v3
	v_cvt_pk_bf16_f32 v3, v4, v5
	global_store_dwordx2 v[14:15], v[2:3], off offset:512
	s_nop 1
	v_mov_b32_e32 v2, v192
	v_mov_b32_e32 v3, v193
	v_mov_b32_e32 v4, v194
	v_mov_b32_e32 v5, v195
	v_mul_f32_e32 v2, v18, v2
	v_mul_f32_e32 v3, v18, v3
	v_mul_f32_e32 v4, v18, v4
	v_mul_f32_e32 v5, v18, v5
	v_cvt_pk_bf16_f32 v2, v2, v3
	v_cvt_pk_bf16_f32 v3, v4, v5
	global_store_dwordx2 v[14:15], v[2:3], off offset:1024
	s_nop 1
	v_mov_b32_e32 v2, v196
	v_mov_b32_e32 v3, v197
	v_mov_b32_e32 v4, v198
	v_mov_b32_e32 v5, v199
	v_mul_f32_e32 v2, v18, v2
	v_mul_f32_e32 v3, v18, v3
	v_mul_f32_e32 v4, v18, v4
	v_mul_f32_e32 v5, v18, v5
	v_cvt_pk_bf16_f32 v2, v2, v3
	v_cvt_pk_bf16_f32 v3, v4, v5
	global_store_dwordx2 v[14:15], v[2:3], off offset:1536
	s_nop 1
	v_mov_b32_e32 v2, v200
	v_mov_b32_e32 v3, v201
	v_mov_b32_e32 v4, v202
	v_mov_b32_e32 v5, v203
	v_mul_f32_e32 v2, v18, v2
	v_mul_f32_e32 v3, v18, v3
	v_mul_f32_e32 v4, v18, v4
	v_mul_f32_e32 v5, v18, v5
	v_cvt_pk_bf16_f32 v2, v2, v3
	v_cvt_pk_bf16_f32 v3, v4, v5
	global_store_dwordx2 v[14:15], v[2:3], off offset:2048
	s_nop 1
	v_mov_b32_e32 v2, v204
	v_mov_b32_e32 v3, v205
	v_mov_b32_e32 v4, v206
	v_mov_b32_e32 v5, v207
	v_mul_f32_e32 v2, v18, v2
	v_mul_f32_e32 v3, v18, v3
	v_mul_f32_e32 v4, v18, v4
	v_mul_f32_e32 v5, v18, v5
	v_cvt_pk_bf16_f32 v2, v2, v3
	v_cvt_pk_bf16_f32 v3, v4, v5
	global_store_dwordx2 v[14:15], v[2:3], off offset:2560
	s_nop 1
	v_mov_b32_e32 v2, v208
	v_mov_b32_e32 v3, v209
	v_mov_b32_e32 v4, v210
	v_mov_b32_e32 v5, v211
	v_mul_f32_e32 v2, v18, v2
	v_mul_f32_e32 v3, v18, v3
	v_mul_f32_e32 v4, v18, v4
	v_mul_f32_e32 v5, v18, v5
	v_cvt_pk_bf16_f32 v2, v2, v3
	v_cvt_pk_bf16_f32 v3, v4, v5
	global_store_dwordx2 v[14:15], v[2:3], off offset:3072
	s_nop 1
	v_mov_b32_e32 v2, v212
	v_mov_b32_e32 v3, v213
	v_mov_b32_e32 v4, v214
	v_mov_b32_e32 v5, v215
	v_add_co_u32_e32 v16, vcc, s6, v10
	v_mul_f32_e32 v2, v18, v2
	v_mul_f32_e32 v3, v18, v3
	v_addc_co_u32_e32 v17, vcc, 0, v11, vcc
	v_mul_f32_e32 v4, v18, v4
	v_mul_f32_e32 v5, v18, v5
	v_cvt_pk_bf16_f32 v2, v2, v3
	v_cvt_pk_bf16_f32 v3, v4, v5
	global_store_dwordx2 v[14:15], v[2:3], off offset:3584
	s_nop 1
	v_mov_b32_e32 v2, v216
	v_mov_b32_e32 v3, v217
	v_mov_b32_e32 v4, v218
	v_mov_b32_e32 v5, v219
	v_add_co_u32_e32 v14, vcc, s1, v14
	v_mul_f32_e32 v2, v18, v2
	s_nop 0
	v_addc_co_u32_e32 v15, vcc, 0, v15, vcc
	v_mul_f32_e32 v3, v18, v3
	v_mul_f32_e32 v4, v18, v4
	v_mul_f32_e32 v5, v18, v5
	v_cvt_pk_bf16_f32 v2, v2, v3
	v_cvt_pk_bf16_f32 v3, v4, v5
	global_store_dwordx2 v[14:15], v[2:3], off
	s_nop 1
	v_mov_b32_e32 v2, v220
	v_mov_b32_e32 v3, v221
	v_mov_b32_e32 v4, v222
	v_mov_b32_e32 v5, v223
	v_add_co_u32_e32 v10, vcc, s7, v10
	v_mul_f32_e32 v2, v18, v2
	v_mul_f32_e32 v3, v18, v3
	v_mul_f32_e32 v4, v18, v4
	v_mul_f32_e32 v5, v18, v5
	v_cvt_pk_bf16_f32 v2, v2, v3
	v_cvt_pk_bf16_f32 v3, v4, v5
	global_store_dwordx2 v[14:15], v[2:3], off offset:512
	s_nop 1
	v_mov_b32_e32 v2, v224
	v_mov_b32_e32 v3, v225
	v_mov_b32_e32 v4, v226
	v_mov_b32_e32 v5, v227
	v_addc_co_u32_e32 v11, vcc, 0, v11, vcc
	v_mul_f32_e32 v2, v18, v2
	v_mul_f32_e32 v3, v18, v3
	v_mul_f32_e32 v4, v18, v4
	v_mul_f32_e32 v5, v18, v5
	v_cvt_pk_bf16_f32 v2, v2, v3
	v_cvt_pk_bf16_f32 v3, v4, v5
	global_store_dwordx2 v[14:15], v[2:3], off offset:1024
	s_nop 1
	v_mov_b32_e32 v2, v228
	v_mov_b32_e32 v3, v229
	v_mov_b32_e32 v4, v230
	v_mov_b32_e32 v5, v231
	v_mul_f32_e32 v2, v18, v2
	v_mul_f32_e32 v3, v18, v3
	v_mul_f32_e32 v4, v18, v4
	v_mul_f32_e32 v5, v18, v5
	v_cvt_pk_bf16_f32 v2, v2, v3
	v_cvt_pk_bf16_f32 v3, v4, v5
	global_store_dwordx2 v[14:15], v[2:3], off offset:1536
	s_nop 1
	v_mov_b32_e32 v2, v232
	v_mov_b32_e32 v3, v233
	v_mov_b32_e32 v4, v234
	v_mov_b32_e32 v5, v235
	v_mul_f32_e32 v2, v18, v2
	v_mul_f32_e32 v3, v18, v3
	v_mul_f32_e32 v4, v18, v4
	v_mul_f32_e32 v5, v18, v5
	v_cvt_pk_bf16_f32 v2, v2, v3
	v_cvt_pk_bf16_f32 v3, v4, v5
	global_store_dwordx2 v[14:15], v[2:3], off offset:2048
	s_nop 1
	v_mov_b32_e32 v2, v236
	v_mov_b32_e32 v3, v237
	v_mov_b32_e32 v4, v238
	v_mov_b32_e32 v5, v239
	v_mul_f32_e32 v2, v18, v2
	v_mul_f32_e32 v3, v18, v3
	v_mul_f32_e32 v4, v18, v4
	v_mul_f32_e32 v5, v18, v5
	v_cvt_pk_bf16_f32 v2, v2, v3
	v_cvt_pk_bf16_f32 v3, v4, v5
	global_store_dwordx2 v[14:15], v[2:3], off offset:2560
	s_nop 1
	v_mov_b32_e32 v2, v240
	v_mov_b32_e32 v3, v241
	v_mov_b32_e32 v4, v242
	v_mov_b32_e32 v5, v243
	v_mul_f32_e32 v2, v18, v2
	v_mul_f32_e32 v3, v18, v3
	v_mul_f32_e32 v4, v18, v4
	v_mul_f32_e32 v5, v18, v5
	v_cvt_pk_bf16_f32 v2, v2, v3
	v_cvt_pk_bf16_f32 v3, v4, v5
	global_store_dwordx2 v[14:15], v[2:3], off offset:3072
	s_nop 1
	v_mov_b32_e32 v2, v244
	v_mov_b32_e32 v3, v245
	v_mov_b32_e32 v4, v246
	v_mov_b32_e32 v5, v247
	v_mul_f32_e32 v2, v18, v2
	v_mul_f32_e32 v3, v18, v3
	v_mul_f32_e32 v4, v18, v4
	v_mul_f32_e32 v5, v18, v5
	v_cvt_pk_bf16_f32 v2, v2, v3
	v_cvt_pk_bf16_f32 v3, v4, v5
	global_store_dwordx2 v[14:15], v[2:3], off offset:3584
	v_lshl_add_u64 v[2:3], v[2:3], 0, s[4:5]
	s_nop 0
	s_or_b32 s4, s0, 1
	s_ashr_i32 s5, s4, 31
	s_lshl_b64 s[8:9], s[4:5], 14
	s_lshl_b64 s[4:5], s[4:5], 13
	s_waitcnt lgkmcnt(0)
	v_lshl_add_u64 v[2:3], v[2:3], 0, s[8:9]
	v_lshl_add_u64 v[6:7], v[2:3], 0, v[8:9]
	v_lshl_add_u64 v[8:9], v[12:13], 0, s[4:5]
	v_add_co_u32_e32 v10, vcc, s1, v6
	s_add_i32 s4, s24, s57
	s_nop 0
	v_addc_co_u32_e32 v11, vcc, 0, v7, vcc
	s_lshl_b32 s4, s4, 3
	s_mov_b64 s[8:9], 0x26000100
	s_movk_i32 s5, 0xffe0
	s_waitcnt vmcnt(16) lgkmcnt(0)
	v_mov_b32_e32 v20, v128
	v_mov_b32_e32 v2, v64
	v_mov_b32_e32 v3, v65
	v_mov_b32_e32 v4, v66
	v_mov_b32_e32 v5, v67
	v_mul_f32_e32 v2, v20, v2
	v_mul_f32_e32 v3, v20, v3
	v_mul_f32_e32 v4, v20, v4
	v_mul_f32_e32 v5, v20, v5
	v_cvt_pk_bf16_f32 v2, v2, v3
	v_cvt_pk_bf16_f32 v3, v4, v5
	global_store_dwordx2 v[8:9], v[2:3], off
	s_nop 1
	v_mov_b32_e32 v2, v68
	v_mov_b32_e32 v3, v69
	v_mov_b32_e32 v4, v70
	v_mov_b32_e32 v5, v71
	v_mul_f32_e32 v2, v20, v2
	v_mul_f32_e32 v3, v20, v3
	v_mul_f32_e32 v4, v20, v4
	v_mul_f32_e32 v5, v20, v5
	v_cvt_pk_bf16_f32 v2, v2, v3
	v_cvt_pk_bf16_f32 v3, v4, v5
	global_store_dwordx2 v[8:9], v[2:3], off offset:512
	s_nop 1
	v_mov_b32_e32 v2, v72
	v_mov_b32_e32 v3, v73
	v_mov_b32_e32 v4, v74
	v_mov_b32_e32 v5, v75
	v_mul_f32_e32 v2, v20, v2
	v_mul_f32_e32 v3, v20, v3
	v_mul_f32_e32 v4, v20, v4
	v_mul_f32_e32 v5, v20, v5
	v_cvt_pk_bf16_f32 v2, v2, v3
	v_cvt_pk_bf16_f32 v3, v4, v5
	global_store_dwordx2 v[8:9], v[2:3], off offset:1024
	s_nop 1
	v_mov_b32_e32 v2, v76
	v_mov_b32_e32 v3, v77
	v_mov_b32_e32 v4, v78
	v_mov_b32_e32 v5, v79
	v_mul_f32_e32 v2, v20, v2
	v_mul_f32_e32 v3, v20, v3
	v_mul_f32_e32 v4, v20, v4
	v_mul_f32_e32 v5, v20, v5
	v_cvt_pk_bf16_f32 v2, v2, v3
	v_cvt_pk_bf16_f32 v3, v4, v5
	global_store_dwordx2 v[8:9], v[2:3], off offset:1536
	s_nop 1
	v_mov_b32_e32 v2, v80
	v_mov_b32_e32 v3, v81
	v_mov_b32_e32 v4, v82
	v_mov_b32_e32 v5, v83
	v_mul_f32_e32 v2, v20, v2
	v_mul_f32_e32 v3, v20, v3
	v_mul_f32_e32 v4, v20, v4
	v_mul_f32_e32 v5, v20, v5
	v_cvt_pk_bf16_f32 v2, v2, v3
	v_cvt_pk_bf16_f32 v3, v4, v5
	global_store_dwordx2 v[8:9], v[2:3], off offset:2048
	s_nop 1
	v_mov_b32_e32 v2, v84
	v_mov_b32_e32 v3, v85
	v_mov_b32_e32 v4, v86
	v_mov_b32_e32 v5, v87
	v_mul_f32_e32 v2, v20, v2
	v_mul_f32_e32 v3, v20, v3
	v_mul_f32_e32 v4, v20, v4
	v_mul_f32_e32 v5, v20, v5
	v_cvt_pk_bf16_f32 v2, v2, v3
	v_cvt_pk_bf16_f32 v3, v4, v5
	global_store_dwordx2 v[8:9], v[2:3], off offset:2560
	s_nop 1
	v_mov_b32_e32 v2, v88
	v_mov_b32_e32 v3, v89
	v_mov_b32_e32 v4, v90
	v_mov_b32_e32 v5, v91
	v_mul_f32_e32 v2, v20, v2
	v_mul_f32_e32 v3, v20, v3
	v_mul_f32_e32 v4, v20, v4
	v_mul_f32_e32 v5, v20, v5
	v_cvt_pk_bf16_f32 v2, v2, v3
	v_cvt_pk_bf16_f32 v3, v4, v5
	global_store_dwordx2 v[8:9], v[2:3], off offset:3072
	s_nop 1
	v_mov_b32_e32 v2, v92
	v_mov_b32_e32 v3, v93
	v_mov_b32_e32 v4, v94
	v_mov_b32_e32 v5, v95
	v_add_co_u32_e32 v10, vcc, s6, v6
	v_mul_f32_e32 v2, v20, v2
	v_mul_f32_e32 v3, v20, v3
	v_addc_co_u32_e32 v11, vcc, 0, v7, vcc
	v_mul_f32_e32 v4, v20, v4
	v_mul_f32_e32 v5, v20, v5
	v_cvt_pk_bf16_f32 v2, v2, v3
	v_cvt_pk_bf16_f32 v3, v4, v5
	global_store_dwordx2 v[8:9], v[2:3], off offset:3584
	s_nop 1
	v_mov_b32_e32 v2, v96
	v_mov_b32_e32 v3, v97
	v_mov_b32_e32 v4, v98
	v_mov_b32_e32 v5, v99
	v_add_co_u32_e32 v16, vcc, s1, v8
	v_lshlrev_b32_e32 v8, 3, v150
	s_nop 0
	v_addc_co_u32_e32 v17, vcc, 0, v9, vcc
	v_add_co_u32_e32 v6, vcc, s7, v6
	v_ashrrev_i32_e32 v9, 31, v8
	s_nop 0
	v_addc_co_u32_e32 v7, vcc, 0, v7, vcc
	v_lshlrev_b64 v[18:19], 1, v[8:9]
	s_mov_b64 s[6:7], 0x4e500100
	s_mov_b64 s[0:1], 0x200
	v_mul_f32_e32 v2, v20, v2
	v_mul_f32_e32 v3, v20, v3
	v_mul_f32_e32 v4, v20, v4
	v_mul_f32_e32 v5, v20, v5
	v_cvt_pk_bf16_f32 v2, v2, v3
	v_cvt_pk_bf16_f32 v3, v4, v5
	global_store_dwordx2 v[16:17], v[2:3], off
	s_nop 1
	v_mov_b32_e32 v2, v100
	v_mov_b32_e32 v3, v101
	v_mov_b32_e32 v4, v102
	v_mov_b32_e32 v5, v103
	v_mul_f32_e32 v2, v20, v2
	v_mul_f32_e32 v3, v20, v3
	v_mul_f32_e32 v4, v20, v4
	v_mul_f32_e32 v5, v20, v5
	v_cvt_pk_bf16_f32 v2, v2, v3
	v_cvt_pk_bf16_f32 v3, v4, v5
	global_store_dwordx2 v[16:17], v[2:3], off offset:512
	s_nop 1
	v_mov_b32_e32 v2, v104
	v_mov_b32_e32 v3, v105
	v_mov_b32_e32 v4, v106
	v_mov_b32_e32 v5, v107
	v_mul_f32_e32 v2, v20, v2
	v_mul_f32_e32 v3, v20, v3
	v_mul_f32_e32 v4, v20, v4
	v_mul_f32_e32 v5, v20, v5
	v_cvt_pk_bf16_f32 v2, v2, v3
	v_cvt_pk_bf16_f32 v3, v4, v5
	global_store_dwordx2 v[16:17], v[2:3], off offset:1024
	s_nop 1
	v_mov_b32_e32 v2, v108
	v_mov_b32_e32 v3, v109
	v_mov_b32_e32 v4, v110
	v_mov_b32_e32 v5, v111
	v_bfi_b32 v10, -16, s4, v134
	v_ashrrev_i32_e32 v11, 31, v10
	v_lshlrev_b64 v[10:11], 13, v[10:11]
	v_or_b32_e32 v10, s10, v10
	v_lshl_add_u64 v[10:11], v[10:11], 0, v[18:19]
	v_lshl_add_u64 v[10:11], s[78:79], 0, v[10:11]
	v_lshl_add_u64 v[10:11], v[10:11], 0, s[8:9]
	v_mul_f32_e32 v2, v20, v2
	v_mul_f32_e32 v3, v20, v3
	v_mul_f32_e32 v4, v20, v4
	v_mul_f32_e32 v5, v20, v5
	v_cvt_pk_bf16_f32 v2, v2, v3
	v_cvt_pk_bf16_f32 v3, v4, v5
	global_store_dwordx2 v[16:17], v[2:3], off offset:1536
	s_nop 1
	v_mov_b32_e32 v2, v112
	v_mov_b32_e32 v3, v113
	v_mov_b32_e32 v4, v114
	v_mov_b32_e32 v5, v115
	v_mul_f32_e32 v2, v20, v2
	v_mul_f32_e32 v3, v20, v3
	v_mul_f32_e32 v4, v20, v4
	v_mul_f32_e32 v5, v20, v5
	v_cvt_pk_bf16_f32 v2, v2, v3
	v_cvt_pk_bf16_f32 v3, v4, v5
	global_store_dwordx2 v[16:17], v[2:3], off offset:2048
	s_nop 1
	v_mov_b32_e32 v2, v116
	v_mov_b32_e32 v3, v117
	v_mov_b32_e32 v4, v118
	v_mov_b32_e32 v5, v119
	v_mul_f32_e32 v2, v20, v2
	v_mul_f32_e32 v3, v20, v3
	v_mul_f32_e32 v4, v20, v4
	v_mul_f32_e32 v5, v20, v5
	v_cvt_pk_bf16_f32 v2, v2, v3
	v_cvt_pk_bf16_f32 v3, v4, v5
	global_store_dwordx2 v[16:17], v[2:3], off offset:2560
	s_nop 1
	v_mov_b32_e32 v2, v120
	v_mov_b32_e32 v3, v121
	v_mov_b32_e32 v4, v122
	v_mov_b32_e32 v5, v123
	v_mul_f32_e32 v2, v20, v2
	v_mul_f32_e32 v3, v20, v3
	v_mul_f32_e32 v4, v20, v4
	v_mul_f32_e32 v5, v20, v5
	v_cvt_pk_bf16_f32 v2, v2, v3
	v_cvt_pk_bf16_f32 v3, v4, v5
	global_store_dwordx2 v[16:17], v[2:3], off offset:3072
	s_nop 1
	v_mov_b32_e32 v12, v124
	v_mov_b32_e32 v13, v125
	v_mov_b32_e32 v14, v126
	v_mov_b32_e32 v15, v127
	v_and_b32_e32 v6, 15, v134
	v_mov_b32_e32 v3, 0
	v_lshl_or_b32 v2, v6, 13, s10
	v_lshl_add_u64 v[8:9], v[2:3], 0, v[18:19]
	v_lshl_add_u64 v[8:9], s[78:79], 0, v[8:9]
	v_mov_b32_e32 v4, v3
	v_mov_b32_e32 v2, v3
	v_lshl_add_u64 v[8:9], v[8:9], 0, s[6:7]
	v_mul_f32_e32 v5, v20, v12
	v_mul_f32_e32 v7, v20, v13
	v_mul_f32_e32 v13, v20, v14
	v_cvt_pk_bf16_f32 v12, v5, v7
	v_mov_b32_e32 v5, v3
	v_mul_f32_e32 v14, v20, v15
	v_cvt_pk_bf16_f32 v13, v13, v14
	global_store_dwordx2 v[16:17], v[12:13], off offset:3584

.LBB0_328:
	s_waitcnt vmcnt(0)
	v_mov_b64_e32 v[6:7], s[92:93]
	flat_load_dwordx2 v[2:3], v[6:7] offset:64 sc0 sc1
	flat_load_dwordx2 v[130:131], v[6:7] offset:80 sc0 sc1
	s_waitcnt vmcnt(0)
	s_lshl_b32 s0, s27, 4
	s_lshl_b32 s1, s26, 1
	s_add_i32 s0, s0, s1
	s_ashr_i32 s1, s0, 31
	s_lshl_b64 s[6:7], s[0:1], 2
	s_lshl_b64 s[8:9], s[0:1], 14
	v_lshlrev_b64 v[8:9], 4, v[134:135]
	v_lshl_add_u64 v[12:13], v[134:135], 3, s[14:15]
	s_lshl_b32 s12, s26, 12
	s_and_b32 s12, s12, 0x1000
	s_waitcnt lgkmcnt(0)
	v_lshl_add_u64 v[2:3], v[2:3], 0, s[6:7]
	flat_load_dword v18, v[2:3]
	global_load_dword v128, v[2:3], off offset:4
	s_nop 0
	v_lshl_add_u64 v[2:3], v[130:131], 0, s[8:9]
	v_lshl_add_u64 v[10:11], v[2:3], 0, v[8:9]
	v_add_co_u32_e32 v212, vcc, 0x1000, v10
	s_nop 1
	v_addc_co_u32_e32 v213, vcc, 0, v11, vcc
	v_add_co_u32_e32 v228, vcc, 0x2000, v10
	s_nop 1
	v_addc_co_u32_e32 v229, vcc, 0, v11, vcc
	v_add_co_u32_e32 v244, vcc, 0x3000, v10
	s_nop 1
	v_addc_co_u32_e32 v245, vcc, 0, v11, vcc
	global_load_dwordx4 v[184:187], v[10:11], off nt
	global_load_dwordx4 v[188:191], v[10:11], off offset:1024 nt
	global_load_dwordx4 v[192:195], v[10:11], off offset:2048 nt
	global_load_dwordx4 v[196:199], v[10:11], off offset:3072 nt
	global_load_dwordx4 v[200:203], v[212:213], off nt
	global_load_dwordx4 v[204:207], v[212:213], off offset:1024 nt
	global_load_dwordx4 v[208:211], v[212:213], off offset:2048 nt
	global_load_dwordx4 v[212:215], v[212:213], off offset:3072 nt
	global_load_dwordx4 v[216:219], v[228:229], off nt
	global_load_dwordx4 v[220:223], v[228:229], off offset:1024 nt
	global_load_dwordx4 v[224:227], v[228:229], off offset:2048 nt
	global_load_dwordx4 v[228:231], v[228:229], off offset:3072 nt
	global_load_dwordx4 v[232:235], v[244:245], off nt
	global_load_dwordx4 v[236:239], v[244:245], off offset:1024 nt
	global_load_dwordx4 v[240:243], v[244:245], off offset:2048 nt
	global_load_dwordx4 v[244:247], v[244:245], off offset:3072 nt
	v_add_co_u32_e32 v76, vcc, 0x4000, v10
	s_nop 1
	v_addc_co_u32_e32 v77, vcc, 0, v11, vcc
	v_add_co_u32_e32 v92, vcc, 0x5000, v10
	s_nop 1
	v_addc_co_u32_e32 v93, vcc, 0, v11, vcc
	v_add_co_u32_e32 v108, vcc, 0x6000, v10
	s_nop 1
	v_addc_co_u32_e32 v109, vcc, 0, v11, vcc
	v_add_co_u32_e32 v124, vcc, 0x7000, v10
	s_nop 1
	v_addc_co_u32_e32 v125, vcc, 0, v11, vcc
	global_load_dwordx4 v[64:67], v[76:77], off nt
	global_load_dwordx4 v[68:71], v[76:77], off offset:1024 nt
	global_load_dwordx4 v[72:75], v[76:77], off offset:2048 nt
	global_load_dwordx4 v[76:79], v[76:77], off offset:3072 nt
	global_load_dwordx4 v[80:83], v[92:93], off nt
	global_load_dwordx4 v[84:87], v[92:93], off offset:1024 nt
	global_load_dwordx4 v[88:91], v[92:93], off offset:2048 nt
	global_load_dwordx4 v[92:95], v[92:93], off offset:3072 nt
	global_load_dwordx4 v[96:99], v[108:109], off nt
	global_load_dwordx4 v[100:103], v[108:109], off offset:1024 nt
	global_load_dwordx4 v[104:107], v[108:109], off offset:2048 nt
	global_load_dwordx4 v[108:111], v[108:109], off offset:3072 nt
	global_load_dwordx4 v[112:115], v[124:125], off nt
	global_load_dwordx4 v[116:119], v[124:125], off offset:1024 nt
	global_load_dwordx4 v[120:123], v[124:125], off offset:2048 nt
	global_load_dwordx4 v[124:127], v[124:125], off offset:3072 nt
	s_lshl_b64 s[8:9], s[0:1], 13
	v_lshl_add_u64 v[14:15], v[12:13], 0, s[8:9]
	s_movk_i32 s1, 0x1000
	v_add_co_u32_e32 v16, vcc, s1, v10
	s_movk_i32 s8, 0x2000
	s_nop 0
	v_addc_co_u32_e32 v17, vcc, 0, v11, vcc
	s_movk_i32 s9, 0x3000
	s_waitcnt vmcnt(16) lgkmcnt(0)
	v_mov_b32_e32 v2, v184
	v_mov_b32_e32 v3, v185
	v_mov_b32_e32 v4, v186
	v_mov_b32_e32 v5, v187
	v_mul_f32_e32 v2, v18, v2
	v_mul_f32_e32 v3, v18, v3
	v_mul_f32_e32 v4, v18, v4
	v_mul_f32_e32 v5, v18, v5
	v_cvt_pk_bf16_f32 v2, v2, v3
	v_cvt_pk_bf16_f32 v3, v4, v5
	global_store_dwordx2 v[14:15], v[2:3], off
	s_nop 1
	v_mov_b32_e32 v2, v188
	v_mov_b32_e32 v3, v189
	v_mov_b32_e32 v4, v190
	v_mov_b32_e32 v5, v191
	v_mul_f32_e32 v2, v18, v2
	v_mul_f32_e32 v3, v18, v3
	v_mul_f32_e32 v4, v18, v4
	v_mul_f32_e32 v5, v18, v5
	v_cvt_pk_bf16_f32 v2, v2, v3
	v_cvt_pk_bf16_f32 v3, v4, v5
	global_store_dwordx2 v[14:15], v[2:3], off offset:512
	s_nop 1
	v_mov_b32_e32 v2, v192
	v_mov_b32_e32 v3, v193
	v_mov_b32_e32 v4, v194
	v_mov_b32_e32 v5, v195
	v_mul_f32_e32 v2, v18, v2
	v_mul_f32_e32 v3, v18, v3
	v_mul_f32_e32 v4, v18, v4
	v_mul_f32_e32 v5, v18, v5
	v_cvt_pk_bf16_f32 v2, v2, v3
	v_cvt_pk_bf16_f32 v3, v4, v5
	global_store_dwordx2 v[14:15], v[2:3], off offset:1024
	s_nop 1
	v_mov_b32_e32 v2, v196
	v_mov_b32_e32 v3, v197
	v_mov_b32_e32 v4, v198
	v_mov_b32_e32 v5, v199
	v_mul_f32_e32 v2, v18, v2
	v_mul_f32_e32 v3, v18, v3
	v_mul_f32_e32 v4, v18, v4
	v_mul_f32_e32 v5, v18, v5
	v_cvt_pk_bf16_f32 v2, v2, v3
	v_cvt_pk_bf16_f32 v3, v4, v5
	global_store_dwordx2 v[14:15], v[2:3], off offset:1536
	s_nop 1
	v_mov_b32_e32 v2, v200
	v_mov_b32_e32 v3, v201
	v_mov_b32_e32 v4, v202
	v_mov_b32_e32 v5, v203
	v_mul_f32_e32 v2, v18, v2
	v_mul_f32_e32 v3, v18, v3
	v_mul_f32_e32 v4, v18, v4
	v_mul_f32_e32 v5, v18, v5
	v_cvt_pk_bf16_f32 v2, v2, v3
	v_cvt_pk_bf16_f32 v3, v4, v5
	global_store_dwordx2 v[14:15], v[2:3], off offset:2048
	s_nop 1
	v_mov_b32_e32 v2, v204
	v_mov_b32_e32 v3, v205
	v_mov_b32_e32 v4, v206
	v_mov_b32_e32 v5, v207
	v_mul_f32_e32 v2, v18, v2
	v_mul_f32_e32 v3, v18, v3
	v_mul_f32_e32 v4, v18, v4
	v_mul_f32_e32 v5, v18, v5
	v_cvt_pk_bf16_f32 v2, v2, v3
	v_cvt_pk_bf16_f32 v3, v4, v5
	global_store_dwordx2 v[14:15], v[2:3], off offset:2560
	s_nop 1
	v_mov_b32_e32 v2, v208
	v_mov_b32_e32 v3, v209
	v_mov_b32_e32 v4, v210
	v_mov_b32_e32 v5, v211
	v_mul_f32_e32 v2, v18, v2
	v_mul_f32_e32 v3, v18, v3
	v_mul_f32_e32 v4, v18, v4
	v_mul_f32_e32 v5, v18, v5
	v_cvt_pk_bf16_f32 v2, v2, v3
	v_cvt_pk_bf16_f32 v3, v4, v5
	global_store_dwordx2 v[14:15], v[2:3], off offset:3072
	s_nop 1
	v_mov_b32_e32 v2, v212
	v_mov_b32_e32 v3, v213
	v_mov_b32_e32 v4, v214
	v_mov_b32_e32 v5, v215
	v_add_co_u32_e32 v16, vcc, s8, v10
	v_mul_f32_e32 v2, v18, v2
	v_mul_f32_e32 v3, v18, v3
	v_addc_co_u32_e32 v17, vcc, 0, v11, vcc
	v_mul_f32_e32 v4, v18, v4
	v_mul_f32_e32 v5, v18, v5
	v_cvt_pk_bf16_f32 v2, v2, v3
	v_cvt_pk_bf16_f32 v3, v4, v5
	global_store_dwordx2 v[14:15], v[2:3], off offset:3584
	s_nop 1
	v_mov_b32_e32 v2, v216
	v_mov_b32_e32 v3, v217
	v_mov_b32_e32 v4, v218
	v_mov_b32_e32 v5, v219
	v_add_co_u32_e32 v14, vcc, s1, v14
	v_mul_f32_e32 v2, v18, v2
	s_nop 0
	v_addc_co_u32_e32 v15, vcc, 0, v15, vcc
	v_mul_f32_e32 v3, v18, v3
	v_mul_f32_e32 v4, v18, v4
	v_mul_f32_e32 v5, v18, v5
	v_cvt_pk_bf16_f32 v2, v2, v3
	v_cvt_pk_bf16_f32 v3, v4, v5
	global_store_dwordx2 v[14:15], v[2:3], off
	s_nop 1
	v_mov_b32_e32 v2, v220
	v_mov_b32_e32 v3, v221
	v_mov_b32_e32 v4, v222
	v_mov_b32_e32 v5, v223
	v_add_co_u32_e32 v10, vcc, s9, v10
	v_mul_f32_e32 v2, v18, v2
	v_mul_f32_e32 v3, v18, v3
	v_mul_f32_e32 v4, v18, v4
	v_mul_f32_e32 v5, v18, v5
	v_cvt_pk_bf16_f32 v2, v2, v3
	v_cvt_pk_bf16_f32 v3, v4, v5
	global_store_dwordx2 v[14:15], v[2:3], off offset:512
	s_nop 1
	v_mov_b32_e32 v2, v224
	v_mov_b32_e32 v3, v225
	v_mov_b32_e32 v4, v226
	v_mov_b32_e32 v5, v227
	v_addc_co_u32_e32 v11, vcc, 0, v11, vcc
	v_mul_f32_e32 v2, v18, v2
	v_mul_f32_e32 v3, v18, v3
	v_mul_f32_e32 v4, v18, v4
	v_mul_f32_e32 v5, v18, v5
	v_cvt_pk_bf16_f32 v2, v2, v3
	v_cvt_pk_bf16_f32 v3, v4, v5
	global_store_dwordx2 v[14:15], v[2:3], off offset:1024
	s_nop 1
	v_mov_b32_e32 v2, v228
	v_mov_b32_e32 v3, v229
	v_mov_b32_e32 v4, v230
	v_mov_b32_e32 v5, v231
	v_mul_f32_e32 v2, v18, v2
	v_mul_f32_e32 v3, v18, v3
	v_mul_f32_e32 v4, v18, v4
	v_mul_f32_e32 v5, v18, v5
	v_cvt_pk_bf16_f32 v2, v2, v3
	v_cvt_pk_bf16_f32 v3, v4, v5
	global_store_dwordx2 v[14:15], v[2:3], off offset:1536
	s_nop 1
	v_mov_b32_e32 v2, v232
	v_mov_b32_e32 v3, v233
	v_mov_b32_e32 v4, v234
	v_mov_b32_e32 v5, v235
	v_mul_f32_e32 v2, v18, v2
	v_mul_f32_e32 v3, v18, v3
	v_mul_f32_e32 v4, v18, v4
	v_mul_f32_e32 v5, v18, v5
	v_cvt_pk_bf16_f32 v2, v2, v3
	v_cvt_pk_bf16_f32 v3, v4, v5
	global_store_dwordx2 v[14:15], v[2:3], off offset:2048
	s_nop 1
	v_mov_b32_e32 v2, v236
	v_mov_b32_e32 v3, v237
	v_mov_b32_e32 v4, v238
	v_mov_b32_e32 v5, v239
	v_mul_f32_e32 v2, v18, v2
	v_mul_f32_e32 v3, v18, v3
	v_mul_f32_e32 v4, v18, v4
	v_mul_f32_e32 v5, v18, v5
	v_cvt_pk_bf16_f32 v2, v2, v3
	v_cvt_pk_bf16_f32 v3, v4, v5
	global_store_dwordx2 v[14:15], v[2:3], off offset:2560
	s_nop 1
	v_mov_b32_e32 v2, v240
	v_mov_b32_e32 v3, v241
	v_mov_b32_e32 v4, v242
	v_mov_b32_e32 v5, v243
	v_mul_f32_e32 v2, v18, v2
	v_mul_f32_e32 v3, v18, v3
	v_mul_f32_e32 v4, v18, v4
	v_mul_f32_e32 v5, v18, v5
	v_cvt_pk_bf16_f32 v2, v2, v3
	v_cvt_pk_bf16_f32 v3, v4, v5
	global_store_dwordx2 v[14:15], v[2:3], off offset:3072
	s_nop 1
	v_mov_b32_e32 v2, v244
	v_mov_b32_e32 v3, v245
	v_mov_b32_e32 v4, v246
	v_mov_b32_e32 v5, v247
	v_mul_f32_e32 v2, v18, v2
	v_mul_f32_e32 v3, v18, v3
	v_mul_f32_e32 v4, v18, v4
	v_mul_f32_e32 v5, v18, v5
	v_cvt_pk_bf16_f32 v2, v2, v3
	v_cvt_pk_bf16_f32 v3, v4, v5
	global_store_dwordx2 v[14:15], v[2:3], off offset:3584
	v_lshl_add_u64 v[2:3], v[2:3], 0, s[6:7]
	s_nop 0
	s_or_b32 s6, s0, 1
	s_ashr_i32 s7, s6, 31
	s_lshl_b64 s[10:11], s[6:7], 14
	s_lshl_b64 s[6:7], s[6:7], 13
	s_waitcnt lgkmcnt(0)
	v_lshl_add_u64 v[2:3], v[2:3], 0, s[10:11]
	v_lshl_add_u64 v[6:7], v[2:3], 0, v[8:9]
	v_lshl_add_u64 v[8:9], v[12:13], 0, s[6:7]
	v_add_co_u32_e32 v10, vcc, s1, v6
	s_add_i32 s6, s26, s57
	s_nop 0
	v_addc_co_u32_e32 v11, vcc, 0, v7, vcc
	s_lshl_b32 s6, s6, 3
	s_mov_b64 s[10:11], 0x26000100
	s_movk_i32 s7, 0xffe0
	s_waitcnt vmcnt(16) lgkmcnt(0)
	v_mov_b32_e32 v20, v128
	v_mov_b32_e32 v2, v64
	v_mov_b32_e32 v3, v65
	v_mov_b32_e32 v4, v66
	v_mov_b32_e32 v5, v67
	v_mul_f32_e32 v2, v20, v2
	v_mul_f32_e32 v3, v20, v3
	v_mul_f32_e32 v4, v20, v4
	v_mul_f32_e32 v5, v20, v5
	v_cvt_pk_bf16_f32 v2, v2, v3
	v_cvt_pk_bf16_f32 v3, v4, v5
	global_store_dwordx2 v[8:9], v[2:3], off
	s_nop 1
	v_mov_b32_e32 v2, v68
	v_mov_b32_e32 v3, v69
	v_mov_b32_e32 v4, v70
	v_mov_b32_e32 v5, v71
	v_mul_f32_e32 v2, v20, v2
	v_mul_f32_e32 v3, v20, v3
	v_mul_f32_e32 v4, v20, v4
	v_mul_f32_e32 v5, v20, v5
	v_cvt_pk_bf16_f32 v2, v2, v3
	v_cvt_pk_bf16_f32 v3, v4, v5
	global_store_dwordx2 v[8:9], v[2:3], off offset:512
	s_nop 1
	v_mov_b32_e32 v2, v72
	v_mov_b32_e32 v3, v73
	v_mov_b32_e32 v4, v74
	v_mov_b32_e32 v5, v75
	v_mul_f32_e32 v2, v20, v2
	v_mul_f32_e32 v3, v20, v3
	v_mul_f32_e32 v4, v20, v4
	v_mul_f32_e32 v5, v20, v5
	v_cvt_pk_bf16_f32 v2, v2, v3
	v_cvt_pk_bf16_f32 v3, v4, v5
	global_store_dwordx2 v[8:9], v[2:3], off offset:1024
	s_nop 1
	v_mov_b32_e32 v2, v76
	v_mov_b32_e32 v3, v77
	v_mov_b32_e32 v4, v78
	v_mov_b32_e32 v5, v79
	v_mul_f32_e32 v2, v20, v2
	v_mul_f32_e32 v3, v20, v3
	v_mul_f32_e32 v4, v20, v4
	v_mul_f32_e32 v5, v20, v5
	v_cvt_pk_bf16_f32 v2, v2, v3
	v_cvt_pk_bf16_f32 v3, v4, v5
	global_store_dwordx2 v[8:9], v[2:3], off offset:1536
	s_nop 1
	v_mov_b32_e32 v2, v80
	v_mov_b32_e32 v3, v81
	v_mov_b32_e32 v4, v82
	v_mov_b32_e32 v5, v83
	v_mul_f32_e32 v2, v20, v2
	v_mul_f32_e32 v3, v20, v3
	v_mul_f32_e32 v4, v20, v4
	v_mul_f32_e32 v5, v20, v5
	v_cvt_pk_bf16_f32 v2, v2, v3
	v_cvt_pk_bf16_f32 v3, v4, v5
	global_store_dwordx2 v[8:9], v[2:3], off offset:2048
	s_nop 1
	v_mov_b32_e32 v2, v84
	v_mov_b32_e32 v3, v85
	v_mov_b32_e32 v4, v86
	v_mov_b32_e32 v5, v87
	v_mul_f32_e32 v2, v20, v2
	v_mul_f32_e32 v3, v20, v3
	v_mul_f32_e32 v4, v20, v4
	v_mul_f32_e32 v5, v20, v5
	v_cvt_pk_bf16_f32 v2, v2, v3
	v_cvt_pk_bf16_f32 v3, v4, v5
	global_store_dwordx2 v[8:9], v[2:3], off offset:2560
	s_nop 1
	v_mov_b32_e32 v2, v88
	v_mov_b32_e32 v3, v89
	v_mov_b32_e32 v4, v90
	v_mov_b32_e32 v5, v91
	v_mul_f32_e32 v2, v20, v2
	v_mul_f32_e32 v3, v20, v3
	v_mul_f32_e32 v4, v20, v4
	v_mul_f32_e32 v5, v20, v5
	v_cvt_pk_bf16_f32 v2, v2, v3
	v_cvt_pk_bf16_f32 v3, v4, v5
	global_store_dwordx2 v[8:9], v[2:3], off offset:3072
	s_nop 1
	v_mov_b32_e32 v2, v92
	v_mov_b32_e32 v3, v93
	v_mov_b32_e32 v4, v94
	v_mov_b32_e32 v5, v95
	v_add_co_u32_e32 v10, vcc, s8, v6
	v_mul_f32_e32 v2, v20, v2
	v_mul_f32_e32 v3, v20, v3
	v_addc_co_u32_e32 v11, vcc, 0, v7, vcc
	v_mul_f32_e32 v4, v20, v4
	v_mul_f32_e32 v5, v20, v5
	v_cvt_pk_bf16_f32 v2, v2, v3
	v_cvt_pk_bf16_f32 v3, v4, v5
	global_store_dwordx2 v[8:9], v[2:3], off offset:3584
	s_nop 1
	v_mov_b32_e32 v2, v96
	v_mov_b32_e32 v3, v97
	v_mov_b32_e32 v4, v98
	v_mov_b32_e32 v5, v99
	v_add_co_u32_e32 v16, vcc, s1, v8
	v_lshlrev_b32_e32 v8, 3, v150
	s_nop 0
	v_addc_co_u32_e32 v17, vcc, 0, v9, vcc
	v_add_co_u32_e32 v6, vcc, s9, v6
	v_ashrrev_i32_e32 v9, 31, v8
	s_nop 0
	v_addc_co_u32_e32 v7, vcc, 0, v7, vcc
	v_lshlrev_b64 v[18:19], 1, v[8:9]
	s_mov_b64 s[8:9], 0x4e500100
	s_mov_b64 s[0:1], 0x200
	v_mul_f32_e32 v2, v20, v2
	v_mul_f32_e32 v3, v20, v3
	v_mul_f32_e32 v4, v20, v4
	v_mul_f32_e32 v5, v20, v5
	v_cvt_pk_bf16_f32 v2, v2, v3
	v_cvt_pk_bf16_f32 v3, v4, v5
	global_store_dwordx2 v[16:17], v[2:3], off
	s_nop 1
	v_mov_b32_e32 v2, v100
	v_mov_b32_e32 v3, v101
	v_mov_b32_e32 v4, v102
	v_mov_b32_e32 v5, v103
	v_mul_f32_e32 v2, v20, v2
	v_mul_f32_e32 v3, v20, v3
	v_mul_f32_e32 v4, v20, v4
	v_mul_f32_e32 v5, v20, v5
	v_cvt_pk_bf16_f32 v2, v2, v3
	v_cvt_pk_bf16_f32 v3, v4, v5
	global_store_dwordx2 v[16:17], v[2:3], off offset:512
	s_nop 1
	v_mov_b32_e32 v2, v104
	v_mov_b32_e32 v3, v105
	v_mov_b32_e32 v4, v106
	v_mov_b32_e32 v5, v107
	v_mul_f32_e32 v2, v20, v2
	v_mul_f32_e32 v3, v20, v3
	v_mul_f32_e32 v4, v20, v4
	v_mul_f32_e32 v5, v20, v5
	v_cvt_pk_bf16_f32 v2, v2, v3
	v_cvt_pk_bf16_f32 v3, v4, v5
	global_store_dwordx2 v[16:17], v[2:3], off offset:1024
	s_nop 1
	v_mov_b32_e32 v2, v108
	v_mov_b32_e32 v3, v109
	v_mov_b32_e32 v4, v110
	v_mov_b32_e32 v5, v111
	v_bfi_b32 v10, -16, s6, v134
	v_ashrrev_i32_e32 v11, 31, v10
	v_lshlrev_b64 v[10:11], 13, v[10:11]
	v_or_b32_e32 v10, s12, v10
	v_lshl_add_u64 v[10:11], v[10:11], 0, v[18:19]
	v_lshl_add_u64 v[10:11], s[78:79], 0, v[10:11]
	v_lshl_add_u64 v[10:11], v[10:11], 0, s[10:11]
	v_mul_f32_e32 v2, v20, v2
	v_mul_f32_e32 v3, v20, v3
	v_mul_f32_e32 v4, v20, v4
	v_mul_f32_e32 v5, v20, v5
	v_cvt_pk_bf16_f32 v2, v2, v3
	v_cvt_pk_bf16_f32 v3, v4, v5
	global_store_dwordx2 v[16:17], v[2:3], off offset:1536
	s_nop 1
	v_mov_b32_e32 v2, v112
	v_mov_b32_e32 v3, v113
	v_mov_b32_e32 v4, v114
	v_mov_b32_e32 v5, v115
	v_mul_f32_e32 v2, v20, v2
	v_mul_f32_e32 v3, v20, v3
	v_mul_f32_e32 v4, v20, v4
	v_mul_f32_e32 v5, v20, v5
	v_cvt_pk_bf16_f32 v2, v2, v3
	v_cvt_pk_bf16_f32 v3, v4, v5
	global_store_dwordx2 v[16:17], v[2:3], off offset:2048
	s_nop 1
	v_mov_b32_e32 v2, v116
	v_mov_b32_e32 v3, v117
	v_mov_b32_e32 v4, v118
	v_mov_b32_e32 v5, v119
	v_mul_f32_e32 v2, v20, v2
	v_mul_f32_e32 v3, v20, v3
	v_mul_f32_e32 v4, v20, v4
	v_mul_f32_e32 v5, v20, v5
	v_cvt_pk_bf16_f32 v2, v2, v3
	v_cvt_pk_bf16_f32 v3, v4, v5
	global_store_dwordx2 v[16:17], v[2:3], off offset:2560
	s_nop 1
	v_mov_b32_e32 v2, v120
	v_mov_b32_e32 v3, v121
	v_mov_b32_e32 v4, v122
	v_mov_b32_e32 v5, v123
	v_mul_f32_e32 v2, v20, v2
	v_mul_f32_e32 v3, v20, v3
	v_mul_f32_e32 v4, v20, v4
	v_mul_f32_e32 v5, v20, v5
	v_cvt_pk_bf16_f32 v2, v2, v3
	v_cvt_pk_bf16_f32 v3, v4, v5
	global_store_dwordx2 v[16:17], v[2:3], off offset:3072
	s_nop 1
	v_mov_b32_e32 v12, v124
	v_mov_b32_e32 v13, v125
	v_mov_b32_e32 v14, v126
	v_mov_b32_e32 v15, v127
	v_and_b32_e32 v6, 15, v134
	v_mov_b32_e32 v3, 0
	v_lshl_or_b32 v2, v6, 13, s12
	v_lshl_add_u64 v[8:9], v[2:3], 0, v[18:19]
	v_lshl_add_u64 v[8:9], s[78:79], 0, v[8:9]
	v_mov_b32_e32 v4, v3
	v_mov_b32_e32 v2, v3
	v_lshl_add_u64 v[8:9], v[8:9], 0, s[8:9]
	v_mul_f32_e32 v5, v20, v12
	v_mul_f32_e32 v7, v20, v13
	v_mul_f32_e32 v13, v20, v14
	v_cvt_pk_bf16_f32 v12, v5, v7
	v_mov_b32_e32 v5, v3
	v_mul_f32_e32 v14, v20, v15
	v_cvt_pk_bf16_f32 v13, v13, v14
	global_store_dwordx2 v[16:17], v[12:13], off offset:3584
